# SB loop VALU trims (persistent ones/addr regs, min3 flag reduce, dead adds removed) + 14 mid heavy units moved to light queues
# speedup vs baseline: 1.0997x; 1.0015x over previous
; __global__ void __launch_bounds__(512) fwd_megakernel(Args a) {
;     ...
;             if (tq0_ == 0) { int slot = -1;
;                 while (tries < 8) { int len = (myq < 4) ? 64 : 192;
;     ...
;                     if (rep) len = 64;
;     ...
;                     if (rep) { if (myq < 4) len = 0; }
;     ...
;  const int idx = (int)atomicAdd(barw + BAR_QCTR + 64 * myq, 1u);
;     ...
;                     if (rep && myq >= 4 && idx < 64) continue;
;     ...
;                     if (idx < len) { slot = (myq << 16) | idx; break; } myq = (myq + 1) & 7; ++tries; }
;                 qslot[0] = slot; }
.LBB0_350:
	v_cmp_gt_i32_e32 vcc, 8, v239
	s_or_b64 s[24:25], s[24:25], exec
	s_and_saveexec_b64 s[26:27], vcc
	s_cbranch_execz .LBB0_349
	v_readlane_b32 s12, v254, 56
	v_lshlrev_b32_e32 v0, 6, v233
	v_readlane_b32 s13, v254, 57
	v_cmp_gt_i32_e32 vcc, 4, v233
	s_nop 0
	v_lshl_add_u64 v[4:5], v[0:1], 2, s[12:13]
	global_atomic_add v0, v[4:5], v231, off sc0
	v_and_b32_e32 v3, 1, v233
	v_lshlrev_b32_e32 v3, 6, v3
	v_add_u32_e32 v3, 0xae, v3
	v_cndmask_b32_e64 v3, v3, 50, vcc
	s_waitcnt vmcnt(0)
	v_cmp_ge_i32_e32 vcc, v0, v3
	s_and_saveexec_b64 s[12:13], vcc
	s_xor_b64 s[36:37], exec, s[12:13]
	v_add_u32_e32 v4, 1, v233
	v_and_b32_e32 v233, 7, v4
	v_add_u32_e32 v239, 1, v239
	s_andn2_saveexec_b64 s[36:37], s[36:37]
	s_cbranch_execz .LBB0_348
	v_lshl_or_b32 v2, v233, 16, v0
	s_branch .LBB0_348

; __global__ void __launch_bounds__(512) fwd_megakernel(Args a) {
;     ...
;             __syncthreads();
;             const int slot = qslot[0];
;             if (slot < 0) break;
;             const int q = slot >> 16, idx = slot & 0xffff;
;             int ub, uh, uq; bool isdf = true;
;             if (q < 4) { ub = q >> 1; uh = 3 - (q & 1); uq = 63 - idx; }
;             else { const int y = q - 4;
;                 if (idx < 64) { ub = y >> 1; uh = 1 - (y & 1); uq = 63 - idx; }
;                 else { const int v = idx - 64; const int bh = 4 * y + (v & 3); ub = bh >> 3; uh = bh & 7; uq = 31 - (v >> 2); isdf = false; } }
.LBB0_356:
	s_or_b64 exec, exec, s[0:1]
	s_add_i32 s0, s4, 0
	v_mov_b32_e32 v0, s0
	s_waitcnt lgkmcnt(0)
	s_barrier
	ds_read_b32 v0, v0
	s_waitcnt lgkmcnt(0)
	v_cmp_gt_i32_e32 vcc, 0, v0
	v_readfirstlane_b32 s4, v0
	s_cbranch_vccnz .LBB0_370
	s_and_b32 s5, s4, 0xffff
	s_cmp_gt_u32 s4, 0x3ffff
	s_mov_b64 s[6:7], -1
	s_cbranch_scc0 .LBB0_367
	s_lshr_b32 s12, s4, 16
	s_add_i32 s12, s12, -4
	s_cmp_lt_u32 s5, 14
	s_cbranch_scc0 .Lmv_not
	s_lshr_b32 s14, s12, 1
	s_and_b32 s16, s12, 1
	s_sub_i32 s16, 3, s16
	s_sub_i32 s15, 31, s5
	s_mov_b64 s[0:1], -1
	s_branch .LBB0_369
.Lmv_not:
	s_add_i32 s5, s5, -14
	s_cmp_lt_u32 s5, 64
	s_cselect_b64 s[0:1], -1, 0
	s_cmp_gt_u32 s5, 63
	s_cbranch_scc0 .LBB0_360
	s_sub_i32 s6, s5, 64
	s_cmp_lt_u32 s6, 0x80
	s_cbranch_scc1 .Lsbq_own
	s_add_i32 s12, s12, -1
	s_add_i32 s6, s6, -32

; __global__ void __launch_bounds__(512) fwd_megakernel(Args a) {
;     ...
;             if (q < 4) { ub = q >> 1; uh = 3 - (q & 1); uq = 63 - idx; }
;             else { const int y = q - 4;
;                 if (idx < 64) { ub = y >> 1; uh = 1 - (y & 1); uq = 63 - idx; }
;                 else { const int v = idx - 64; const int bh = 4 * y + (v & 3); ub = bh >> 3; uh = bh & 7; uq = 31 - (v >> 2); isdf = false; } }
.LBB0_367:
	s_and_b64 vcc, exec, s[6:7]
	s_cbranch_vccz .LBB0_363
	s_bfe_u32 s0, s4, 0x10010
	s_lshr_b32 s14, s4, 17
	s_xor_b32 s16, s0, 3
	s_cmp_lt_u32 s5, 32
	s_cbranch_scc1 .Lhv_ok
	s_add_i32 s5, s5, 14

; #define MFMA32(a, b, c) __builtin_amdgcn_mfma_f32_32x32x16_bf16((a), (b), (c), 0, 0, 0)
; DI float ex2(float x) { return __builtin_amdgcn_exp2f(x); }
; template <int S> DI bf16x8 pack8(const f32x16& x) { u32x4 p; p[0] = cvtpk(x[8 * S], x[8 * S + 1]); p[1] = cvtpk(x[8 * S + 2], x[8 * S + 3]); p[2] = cvtpk(x[8 * S + 4], x[8 * S + 5]); p[3] = cvtpk(x[8 * S + 6], x[8 * S + 7]); return __builtin_bit_cast(bf16x8, p); }
; #define SB_PV(ks, pa) { const bf16x8 v0 = ldsv(Vt + off128(r32, 2 * (ks) + hi)), v1 = ldsv(Vt + off128(32 + r32, 2 * (ks) + hi)); o0 = MFMA32(v0, pa, o0); o1 = MFMA32(v1, pa, o1); }
; DI void sb_unit(LAS char* lds, int b, int h, int qb, const bf16_t* __restrict__ Q, const bf16_t* __restrict__ K, const bf16_t* __restrict__ VT, const bf16_t* __restrict__ G, bf16_t* __restrict__ MIX) {
;     ...
;             C0 = MFMA32(tp0, Lh0, C0); C0 = MFMA32(tp1, Lh1, C0); C0 = MFMA32(ones, Lh2, C0); C0 = MFMA32(ones, Lh3, C0);
;             C1 = MFMA32(tp0, Lh2, C1); C1 = MFMA32(tp1, Lh3, C1);
;             const float cn = C0[0] + L0[0];
;             carry = __shfl(cn, r32, 64);
; #pragma unroll
;             for (int r = 0; r < 16; ++r) { p0[r] = ex2(p0[r] + C0[r]); p1[r] = ex2(p1[r] + C1[r]); }
;             const bf16x8 pa0 = pack8<0>(p0), pa1 = pack8<1>(p0), pa2 = pack8<0>(p1), pa3 = pack8<1>(p1);
;     ...
;             SB_PV(0, pa0) SB_PV(1, pa1) SB_PV(2, pa2) SB_PV(3, pa3)
;     ...
;             done = __all(carry < -152.f) ? 1 : 0;
;         }
;         if (lane == 0) flags[(it & 1) * 8 + wid] = done;
.LBB0_414:
	v_readlane_b32 s4, v254, 48
	s_lshl_b32 s0, s27, 2
	v_and_b32_e32 v35, 63, v35
	s_add_i32 s27, s0, 0
	v_cmp_eq_u32_e64 s[36:37], 0, v35
	s_add_i32 s27, s27, 0x20000
	s_and_saveexec_b64 s[0:1], s[36:37]
	v_mov_b32_e32 v35, s27
	ds_write_b32 v35, v36
	s_or_b64 exec, exec, s[0:1]
	s_lshl_b32 s0, s38, 6
	s_add_i32 s98, s38, -2
	s_lshr_b32 s46, s25, 11
	s_lshl_b32 s46, s46, 6
	s_add_i32 s39, s0, s46
	s_add_i32 s39, s39, 0xffffff00
	s_mov_b32 s38, 1
	s_movk_i32 s40, 0x4000
	s_mov_b32 s41, 8
	s_mov_b32 s5, s4
	v_mov_b64_e32 v[240:241], s[4:5]
	v_mov_b64_e32 v[242:243], s[4:5]
	v_and_or_b32 v229, v238, 64, v100
	v_lshlrev_b32_e32 v229, 2, v229
	s_branch .LBB0_418

; #define LAS __attribute__((address_space(3)))
; #define WAIT_BAR0() asm volatile("s_waitcnt vmcnt(0) lgkmcnt(0)\n\ts_barrier" ::: "memory")
; DI void sb_unit(LAS char* lds, int b, int h, int qb, const bf16_t* __restrict__ Q, const bf16_t* __restrict__ K, const bf16_t* __restrict__ VT, const bf16_t* __restrict__ G, bf16_t* __restrict__ MIX) {
;     ...
;     for (int T = nt - 1, it = 0; T >= 0; --T, ++it) {
;         WAIT_BAR0();
;         if (it > 0) { volatile LAS int* fl = flags + ((it & 1) ^ 1) * 8; const int all = fl[0] & fl[1] & fl[2] & fl[3] & fl[4] & fl[5] & fl[6] & fl[7]; if (all) break; }
.LBB0_418:
	s_andn2_b32 s0, 8, s41
	s_lshl_b32 s0, s0, 2
	s_add_i32 s0, s0, 0
	s_add_i32 s0, s0, 0x20000
	s_waitcnt vmcnt(0) lgkmcnt(0)
	s_barrier
	v_mov_b32_e32 v35, s0
	ds_read_b128 v[108:111], v35
	ds_read_b128 v[112:115], v35 offset:16
	s_waitcnt lgkmcnt(0)
	v_min3_u32 v37, v108, v109, v110
	v_min3_u32 v38, v111, v112, v113
	v_min3_u32 v37, v37, v114, v115
	v_min_u32_e32 v35, v37, v38
	v_cmp_ne_u32_e32 vcc, 0, v35
	s_cbranch_vccz .LBB0_420
	s_cbranch_execz .LBB0_418
	s_branch .LBB0_372

; #define LAS __attribute__((address_space(3)))
; #define MFMA32(a, b, c) __builtin_amdgcn_mfma_f32_32x32x16_bf16((a), (b), (c), 0, 0, 0)
; DI int crow(int r, int hi) { return (r & 3) + 8 * (r >> 2) + 4 * hi; }
; DI float ex2(float x) { return __builtin_amdgcn_exp2f(x); }
; DI float lg2(float x) { return __builtin_amdgcn_logf(x); }
; DI void sb_unit(LAS char* lds, int b, int h, int qb, const bf16_t* __restrict__ Q, const bf16_t* __restrict__ K, const bf16_t* __restrict__ VT, const bf16_t* __restrict__ G, bf16_t* __restrict__ MIX) {
;     ...
;         const LAS char* Kt = lds + (it & 1) * 16384; const LAS char* Vt = Kt + 8192;
;         const int kv0 = 64 * T;
;         if (kv0 < qw0 + 31 && !done) {
;             f32x16 p0 = splat16(0.f), p1 = splat16(0.f);
; #pragma unroll
;             for (int d0 = 0; d0 < 4; ++d0) { const bf16x8 k0 = ldsv(Kt + off128(r32, 2 * d0 + hi)), k1 = ldsv(Kt + off128(32 + r32, 2 * d0 + hi)); p0 = MFMA32(k0, qf[d0], p0); p1 = MFMA32(k1, qf[d0], p1); }
;             const bool diag = (kv0 + 63 >= qw0);
;             f32x16 L0, L1;
; #pragma unroll
;             for (int r = 0; r < 16; ++r) {
;                 { const float z = p0[r]; const float lg = (z > 30.f) ? z : lg2(1.0f + ex2(z)); const bool valid = !diag || (kv0 + crow(r, hi) < tq); L0[r] = valid ? -lg : 0.f; p0[r] = valid ? (z - lg) : -1e30f; }
;                 { const float z = p1[r]; const float lg = (z > 30.f) ? z : lg2(1.0f + ex2(z)); const bool valid = !diag || (kv0 + 32 + crow(r, hi) < tq); L1[r] = valid ? -lg : 0.f; p1[r] = valid ? (z - lg) : -1e30f; }
;             }
.LBB0_422:
	s_and_b32 s42, s38, 1
	s_cmp_lt_i32 s39, 0
	s_cbranch_scc1 .LBB0_424
	s_cmp_ge_i32 s39, s26
	s_cselect_b64 s[0:1], -1, 0
	v_cmp_ne_u32_e32 vcc, 0, v36
	s_or_b64 s[0:1], s[0:1], vcc
	s_and_b64 vcc, exec, s[0:1]
	s_cbranch_vccnz .LBB0_424
	s_lshr_b32 s0, s39, 6
	s_and_b32 s0, s0, 7
	s_lshl_b32 s0, s0, 14
	s_add_i32 s43, s0, 0
	v_add3_u32 v225, s43, v104, v103
	v_add3_u32 v226, s43, v105, v103
	ds_read_b128 v[36:39], v225
	ds_read_b128 v[40:43], v225 offset:4096
	v_add3_u32 v227, s43, v106, v103
	ds_read_b128 v[108:111], v226
	ds_read_b128 v[112:115], v226 offset:4096
	v_add3_u32 v228, s43, v107, v103
	s_add_i32 s0, s39, 63
	s_waitcnt lgkmcnt(3)
	v_mfma_f32_32x32x16_bf16 v[52:67], v[36:39], v[68:71], 0
	s_cmp_lt_i32 s0, s24
	s_cselect_b64 s[0:1], -1, 0
	s_waitcnt lgkmcnt(2)
	v_mfma_f32_32x32x16_bf16 v[36:51], v[40:43], v[68:71], 0
	s_waitcnt lgkmcnt(1)
	v_mfma_f32_32x32x16_bf16 v[52:67], v[108:111], v[72:75], v[52:67]
	s_waitcnt lgkmcnt(0)
	v_mfma_f32_32x32x16_bf16 v[36:51], v[112:115], v[72:75], v[36:51]
	ds_read_b128 v[108:111], v227
	ds_read_b128 v[112:115], v227 offset:4096
	s_waitcnt lgkmcnt(1)
	v_mfma_f32_32x32x16_bf16 v[52:67], v[108:111], v[76:79], v[52:67]
	s_waitcnt lgkmcnt(0)
	v_mfma_f32_32x32x16_bf16 v[36:51], v[112:115], v[76:79], v[36:51]
	ds_read_b128 v[108:111], v228
	ds_read_b128 v[112:115], v228 offset:4096
	s_waitcnt lgkmcnt(1)
	v_mfma_f32_32x32x16_bf16 v[52:67], v[108:111], v[80:83], v[52:67]
	s_waitcnt lgkmcnt(0)
	v_mfma_f32_32x32x16_bf16 v[36:51], v[112:115], v[80:83], v[36:51]
	s_nop 9
	v_min_f32_e32 v52, 0x42fc0000, v52
	v_min_f32_e32 v53, 0x42fc0000, v53
	v_min_f32_e32 v54, 0x42fc0000, v54
	v_min_f32_e32 v55, 0x42fc0000, v55
	v_min_f32_e32 v56, 0x42fc0000, v56
	v_min_f32_e32 v57, 0x42fc0000, v57
	v_min_f32_e32 v58, 0x42fc0000, v58
	v_min_f32_e32 v59, 0x42fc0000, v59
	v_min_f32_e32 v60, 0x42fc0000, v60
	v_min_f32_e32 v61, 0x42fc0000, v61
	v_min_f32_e32 v62, 0x42fc0000, v62
	v_min_f32_e32 v63, 0x42fc0000, v63
	v_min_f32_e32 v64, 0x42fc0000, v64
	v_min_f32_e32 v65, 0x42fc0000, v65
	v_min_f32_e32 v66, 0x42fc0000, v66
	v_min_f32_e32 v67, 0x42fc0000, v67
	v_min_f32_e32 v36, 0x42fc0000, v36
	v_min_f32_e32 v37, 0x42fc0000, v37
	v_min_f32_e32 v38, 0x42fc0000, v38
	v_min_f32_e32 v39, 0x42fc0000, v39
	v_min_f32_e32 v40, 0x42fc0000, v40
	v_min_f32_e32 v41, 0x42fc0000, v41
	v_min_f32_e32 v42, 0x42fc0000, v42
	v_min_f32_e32 v43, 0x42fc0000, v43
	v_min_f32_e32 v44, 0x42fc0000, v44
	v_min_f32_e32 v45, 0x42fc0000, v45
	v_min_f32_e32 v46, 0x42fc0000, v46
	v_min_f32_e32 v47, 0x42fc0000, v47
	v_min_f32_e32 v48, 0x42fc0000, v48
	v_min_f32_e32 v49, 0x42fc0000, v49
	v_min_f32_e32 v50, 0x42fc0000, v50
	v_min_f32_e32 v51, 0x42fc0000, v51
	v_exp_f32_e32 v160, v52
	v_exp_f32_e32 v161, v53
	v_exp_f32_e32 v162, v54
	v_exp_f32_e32 v163, v55
	v_exp_f32_e32 v164, v56
	v_exp_f32_e32 v165, v57
	v_exp_f32_e32 v166, v58
	v_exp_f32_e32 v167, v59
	v_exp_f32_e32 v168, v60
	v_exp_f32_e32 v169, v61
	v_exp_f32_e32 v170, v62
	v_exp_f32_e32 v171, v63
	v_exp_f32_e32 v172, v64
	v_exp_f32_e32 v173, v65
	v_exp_f32_e32 v174, v66
	v_exp_f32_e32 v175, v67
	v_exp_f32_e32 v176, v36
	v_exp_f32_e32 v177, v37
	v_exp_f32_e32 v178, v38
	v_exp_f32_e32 v179, v39
	v_exp_f32_e32 v180, v40
	v_exp_f32_e32 v181, v41
	v_exp_f32_e32 v182, v42
	v_exp_f32_e32 v183, v43
	v_exp_f32_e32 v184, v44
	v_exp_f32_e32 v185, v45
	v_exp_f32_e32 v186, v46
	v_exp_f32_e32 v187, v47
	v_exp_f32_e32 v188, v48
	v_exp_f32_e32 v189, v49
	v_exp_f32_e32 v190, v50
	v_exp_f32_e32 v191, v51
	v_add_f32_e32 v160, 1.0, v160
	v_add_f32_e32 v161, 1.0, v161
	v_add_f32_e32 v162, 1.0, v162
	v_add_f32_e32 v163, 1.0, v163
	v_add_f32_e32 v164, 1.0, v164
	v_add_f32_e32 v165, 1.0, v165
	v_add_f32_e32 v166, 1.0, v166
	v_add_f32_e32 v167, 1.0, v167
	v_add_f32_e32 v168, 1.0, v168
	v_add_f32_e32 v169, 1.0, v169
	v_add_f32_e32 v170, 1.0, v170
	v_add_f32_e32 v171, 1.0, v171
	v_add_f32_e32 v172, 1.0, v172
	v_add_f32_e32 v173, 1.0, v173
	v_add_f32_e32 v174, 1.0, v174
	v_add_f32_e32 v175, 1.0, v175
	v_add_f32_e32 v176, 1.0, v176
	v_add_f32_e32 v177, 1.0, v177
	v_add_f32_e32 v178, 1.0, v178
	v_add_f32_e32 v179, 1.0, v179
	v_add_f32_e32 v180, 1.0, v180
	v_add_f32_e32 v181, 1.0, v181
	v_add_f32_e32 v182, 1.0, v182
	v_add_f32_e32 v183, 1.0, v183
	v_add_f32_e32 v184, 1.0, v184
	v_add_f32_e32 v185, 1.0, v185
	v_add_f32_e32 v186, 1.0, v186
	v_add_f32_e32 v187, 1.0, v187
	v_add_f32_e32 v188, 1.0, v188
	v_add_f32_e32 v189, 1.0, v189
	v_add_f32_e32 v190, 1.0, v190
	v_add_f32_e32 v191, 1.0, v191
	v_log_f32_e32 v160, v160
	v_log_f32_e32 v161, v161
	v_log_f32_e32 v162, v162
	v_log_f32_e32 v163, v163
	v_log_f32_e32 v164, v164
	v_log_f32_e32 v165, v165
	v_log_f32_e32 v166, v166
	v_log_f32_e32 v167, v167
	v_log_f32_e32 v168, v168
	v_log_f32_e32 v169, v169
	v_log_f32_e32 v170, v170
	v_log_f32_e32 v171, v171
	v_log_f32_e32 v172, v172
	v_log_f32_e32 v173, v173
	v_log_f32_e32 v174, v174
	v_log_f32_e32 v175, v175
	v_log_f32_e32 v176, v176
	v_log_f32_e32 v177, v177
	v_log_f32_e32 v178, v178
	v_log_f32_e32 v179, v179
	v_log_f32_e32 v180, v180
	v_log_f32_e32 v181, v181
	v_log_f32_e32 v182, v182
	v_log_f32_e32 v183, v183
	v_log_f32_e32 v184, v184
	v_log_f32_e32 v185, v185
	v_log_f32_e32 v186, v186
	v_log_f32_e32 v187, v187
	v_log_f32_e32 v188, v188
	v_log_f32_e32 v189, v189
	v_log_f32_e32 v190, v190
	v_log_f32_e32 v191, v191
	s_and_b64 vcc, exec, s[0:1]
	s_cbranch_vccz .Lsb_sp_diag
	v_sub_f32_e32 v109, 0, v160
	v_cvt_pk_bf16_f32 v138, -v160, -v161
	v_cvt_pk_bf16_f32 v139, -v162, -v163
	v_cvt_pk_bf16_f32 v140, -v164, -v165
	v_cvt_pk_bf16_f32 v141, -v166, -v167
	v_cvt_pk_bf16_f32 v142, -v168, -v169
	v_cvt_pk_bf16_f32 v143, -v170, -v171
	v_cvt_pk_bf16_f32 v144, -v172, -v173
	v_cvt_pk_bf16_f32 v145, -v174, -v175
	v_cvt_pk_bf16_f32 v146, -v176, -v177
	v_cvt_pk_bf16_f32 v147, -v178, -v179
	v_cvt_pk_bf16_f32 v148, -v180, -v181
	v_cvt_pk_bf16_f32 v149, -v182, -v183
	v_cvt_pk_bf16_f32 v150, -v184, -v185
	v_cvt_pk_bf16_f32 v151, -v186, -v187
	v_cvt_pk_bf16_f32 v152, -v188, -v189
	v_cvt_pk_bf16_f32 v153, -v190, -v191
	v_sub_f32_e32 v108, v52, v160
	v_sub_f32_e32 v111, v53, v161
	v_sub_f32_e32 v113, v54, v162
	v_sub_f32_e32 v115, v55, v163
	v_sub_f32_e32 v117, v56, v164
	v_sub_f32_e32 v119, v57, v165
	v_sub_f32_e32 v121, v58, v166
	v_sub_f32_e32 v123, v59, v167
	v_sub_f32_e32 v125, v60, v168
	v_sub_f32_e32 v127, v61, v169
	v_sub_f32_e32 v129, v62, v170
	v_sub_f32_e32 v131, v63, v171
	v_sub_f32_e32 v133, v64, v172
	v_sub_f32_e32 v135, v65, v173
	v_sub_f32_e32 v66, v66, v174
	v_sub_f32_e32 v155, v67, v175
	v_sub_f32_e32 v110, v36, v176
	v_sub_f32_e32 v112, v37, v177
	v_sub_f32_e32 v114, v38, v178
	v_sub_f32_e32 v116, v39, v179
	v_sub_f32_e32 v118, v40, v180
	v_sub_f32_e32 v120, v41, v181
	v_sub_f32_e32 v122, v42, v182
	v_sub_f32_e32 v124, v43, v183
	v_sub_f32_e32 v126, v44, v184
	v_sub_f32_e32 v128, v45, v185
	v_sub_f32_e32 v130, v46, v186
	v_sub_f32_e32 v132, v47, v187
	v_sub_f32_e32 v134, v48, v188
	v_sub_f32_e32 v136, v49, v189
	v_sub_f32_e32 v154, v50, v190
	v_sub_f32_e32 v156, v51, v191
	s_branch .Lsb_sp_join
; DI int crow(int r, int hi) { return (r & 3) + 8 * (r >> 2) + 4 * hi; }
; DI float ex2(float x) { return __builtin_amdgcn_exp2f(x); }
; DI float lg2(float x) { return __builtin_amdgcn_logf(x); }
; template <int S> DI bf16x8 pack8(const f32x16& x) { u32x4 p; p[0] = cvtpk(x[8 * S], x[8 * S + 1]); p[1] = cvtpk(x[8 * S + 2], x[8 * S + 3]); p[2] = cvtpk(x[8 * S + 4], x[8 * S + 5]); p[3] = cvtpk(x[8 * S + 6], x[8 * S + 7]); return __builtin_bit_cast(bf16x8, p); }
; DI void sb_unit(LAS char* lds, int b, int h, int qb, const bf16_t* __restrict__ Q, const bf16_t* __restrict__ K, const bf16_t* __restrict__ VT, const bf16_t* __restrict__ G, bf16_t* __restrict__ MIX) {
;     ...
;             const bool diag = (kv0 + 63 >= qw0);
;             f32x16 L0, L1;
; #pragma unroll
;             for (int r = 0; r < 16; ++r) {
;                 { const float z = p0[r]; const float lg = (z > 30.f) ? z : lg2(1.0f + ex2(z)); const bool valid = !diag || (kv0 + crow(r, hi) < tq); L0[r] = valid ? -lg : 0.f; p0[r] = valid ? (z - lg) : -1e30f; }
;                 { const float z = p1[r]; const float lg = (z > 30.f) ? z : lg2(1.0f + ex2(z)); const bool valid = !diag || (kv0 + 32 + crow(r, hi) < tq); L1[r] = valid ? -lg : 0.f; p1[r] = valid ? (z - lg) : -1e30f; }
;             }
;             const bf16x8 Lh0 = pack8<0>(L0), Lh1 = pack8<1>(L0), Lh2 = pack8<0>(L1), Lh3 = pack8<1>(L1);
.Lsb_sp_diag:
	v_add_u32_e32 v35, s39, v102
	v_sub_u32_e32 v224, v101, v35
	v_cmp_gt_i32_e64 s[52:53], v224, 0
	v_cmp_gt_i32_e64 s[54:55], v224, 1
	v_cmp_gt_i32_e64 s[56:57], v224, 2
	v_cmp_gt_i32_e64 s[58:59], v224, 3
	v_cmp_gt_i32_e64 s[60:61], v224, 8
	v_cmp_gt_i32_e64 s[62:63], v224, 9
	v_cmp_gt_i32_e64 s[64:65], v224, 10
	v_cmp_gt_i32_e64 s[66:67], v224, 11
	v_cmp_gt_i32_e64 s[68:69], v224, 16
	v_cmp_gt_i32_e64 s[70:71], v224, 17
	v_cndmask_b32_e64 v192, 0, -v160, s[52:53]
	v_cndmask_b32_e64 v193, 0, -v161, s[54:55]
	v_cndmask_b32_e64 v194, 0, -v162, s[56:57]
	v_cndmask_b32_e64 v195, 0, -v163, s[58:59]
	v_cndmask_b32_e64 v196, 0, -v164, s[60:61]
	v_cndmask_b32_e64 v197, 0, -v165, s[62:63]
	v_cndmask_b32_e64 v198, 0, -v166, s[64:65]
	v_cndmask_b32_e64 v199, 0, -v167, s[66:67]
	v_cndmask_b32_e64 v200, 0, -v168, s[68:69]
	v_cndmask_b32_e64 v201, 0, -v169, s[70:71]
	v_sub_f32_e32 v160, v52, v160
	v_sub_f32_e32 v161, v53, v161
	v_sub_f32_e32 v162, v54, v162
	v_sub_f32_e32 v163, v55, v163
	v_sub_f32_e32 v164, v56, v164
	v_sub_f32_e32 v165, v57, v165
	v_sub_f32_e32 v166, v58, v166
	v_sub_f32_e32 v167, v59, v167
	v_sub_f32_e32 v168, v60, v168
	v_sub_f32_e32 v169, v61, v169
	v_cndmask_b32_e64 v108, v237, v160, s[52:53]
	v_cndmask_b32_e64 v111, v237, v161, s[54:55]
	v_cndmask_b32_e64 v113, v237, v162, s[56:57]
	v_cndmask_b32_e64 v115, v237, v163, s[58:59]
	v_cndmask_b32_e64 v117, v237, v164, s[60:61]
	v_cndmask_b32_e64 v119, v237, v165, s[62:63]
	v_cndmask_b32_e64 v121, v237, v166, s[64:65]
	v_cndmask_b32_e64 v123, v237, v167, s[66:67]
	v_cndmask_b32_e64 v125, v237, v168, s[68:69]
	v_cndmask_b32_e64 v127, v237, v169, s[70:71]
	v_cmp_gt_i32_e64 s[52:53], v224, 18
	v_cmp_gt_i32_e64 s[54:55], v224, 19
	v_cmp_gt_i32_e64 s[56:57], v224, 24
	v_cmp_gt_i32_e64 s[58:59], v224, 25
	v_cmp_gt_i32_e64 s[60:61], v224, 26
	v_cmp_gt_i32_e64 s[62:63], v224, 27
	v_cmp_gt_i32_e64 s[64:65], v224, 32
	v_cmp_gt_i32_e64 s[66:67], v224, 33
	v_cmp_gt_i32_e64 s[68:69], v224, 34
	v_cmp_gt_i32_e64 s[70:71], v224, 35
	v_cndmask_b32_e64 v202, 0, -v170, s[52:53]
	v_cndmask_b32_e64 v203, 0, -v171, s[54:55]
	v_cndmask_b32_e64 v204, 0, -v172, s[56:57]
	v_cndmask_b32_e64 v205, 0, -v173, s[58:59]
	v_cndmask_b32_e64 v206, 0, -v174, s[60:61]
	v_cndmask_b32_e64 v207, 0, -v175, s[62:63]
	v_cndmask_b32_e64 v208, 0, -v176, s[64:65]
	v_cndmask_b32_e64 v209, 0, -v177, s[66:67]
	v_cndmask_b32_e64 v210, 0, -v178, s[68:69]
	v_cndmask_b32_e64 v211, 0, -v179, s[70:71]
	v_sub_f32_e32 v170, v62, v170
	v_sub_f32_e32 v171, v63, v171
	v_sub_f32_e32 v172, v64, v172
	v_sub_f32_e32 v173, v65, v173
	v_sub_f32_e32 v174, v66, v174
	v_sub_f32_e32 v175, v67, v175
	v_sub_f32_e32 v176, v36, v176
	v_sub_f32_e32 v177, v37, v177
	v_sub_f32_e32 v178, v38, v178
	v_sub_f32_e32 v179, v39, v179
	v_cndmask_b32_e64 v129, v237, v170, s[52:53]
	v_cndmask_b32_e64 v131, v237, v171, s[54:55]
	v_cndmask_b32_e64 v133, v237, v172, s[56:57]
	v_cndmask_b32_e64 v135, v237, v173, s[58:59]
	v_cndmask_b32_e64 v66, v237, v174, s[60:61]
	v_cndmask_b32_e64 v155, v237, v175, s[62:63]
	v_cndmask_b32_e64 v110, v237, v176, s[64:65]
	v_cndmask_b32_e64 v112, v237, v177, s[66:67]
	v_cndmask_b32_e64 v114, v237, v178, s[68:69]
	v_cndmask_b32_e64 v116, v237, v179, s[70:71]
	v_cmp_gt_i32_e64 s[52:53], v224, 40
	v_cmp_gt_i32_e64 s[54:55], v224, 41
	v_cmp_gt_i32_e64 s[56:57], v224, 42
	v_cmp_gt_i32_e64 s[58:59], v224, 43
	v_cmp_gt_i32_e64 s[60:61], v224, 48
	v_cmp_gt_i32_e64 s[62:63], v224, 49
	v_cmp_gt_i32_e64 s[64:65], v224, 50
	v_cmp_gt_i32_e64 s[66:67], v224, 51
	v_cmp_gt_i32_e64 s[68:69], v224, 56
	v_cmp_gt_i32_e64 s[70:71], v224, 57
	v_cndmask_b32_e64 v212, 0, -v180, s[52:53]
	v_cndmask_b32_e64 v213, 0, -v181, s[54:55]
	v_cndmask_b32_e64 v214, 0, -v182, s[56:57]
	v_cndmask_b32_e64 v215, 0, -v183, s[58:59]
	v_cndmask_b32_e64 v216, 0, -v184, s[60:61]
	v_cndmask_b32_e64 v217, 0, -v185, s[62:63]
	v_cndmask_b32_e64 v218, 0, -v186, s[64:65]
	v_cndmask_b32_e64 v219, 0, -v187, s[66:67]
	v_cndmask_b32_e64 v220, 0, -v188, s[68:69]
	v_cndmask_b32_e64 v221, 0, -v189, s[70:71]
	v_sub_f32_e32 v180, v40, v180
	v_sub_f32_e32 v181, v41, v181
	v_sub_f32_e32 v182, v42, v182
	v_sub_f32_e32 v183, v43, v183
	v_sub_f32_e32 v184, v44, v184
	v_sub_f32_e32 v185, v45, v185
	v_sub_f32_e32 v186, v46, v186
	v_sub_f32_e32 v187, v47, v187
	v_sub_f32_e32 v188, v48, v188
	v_sub_f32_e32 v189, v49, v189
	v_cndmask_b32_e64 v118, v237, v180, s[52:53]
	v_cndmask_b32_e64 v120, v237, v181, s[54:55]
	v_cndmask_b32_e64 v122, v237, v182, s[56:57]
	v_cndmask_b32_e64 v124, v237, v183, s[58:59]
	v_cndmask_b32_e64 v126, v237, v184, s[60:61]
	v_cndmask_b32_e64 v128, v237, v185, s[62:63]
	v_cndmask_b32_e64 v130, v237, v186, s[64:65]
	v_cndmask_b32_e64 v132, v237, v187, s[66:67]
	v_cndmask_b32_e64 v134, v237, v188, s[68:69]
	v_cndmask_b32_e64 v136, v237, v189, s[70:71]
	v_cmp_gt_i32_e64 s[52:53], v224, 58
	v_cmp_gt_i32_e64 s[54:55], v224, 59
	s_nop 1
	v_cndmask_b32_e64 v222, 0, -v190, s[52:53]
	v_cndmask_b32_e64 v223, 0, -v191, s[54:55]
	v_sub_f32_e32 v190, v50, v190
	v_sub_f32_e32 v191, v51, v191
	v_cndmask_b32_e64 v154, v237, v190, s[52:53]
	v_cndmask_b32_e64 v156, v237, v191, s[54:55]
	v_mov_b32_e32 v109, v192
	v_cvt_pk_bf16_f32 v138, v192, v193
	v_cvt_pk_bf16_f32 v139, v194, v195
	v_cvt_pk_bf16_f32 v140, v196, v197
	v_cvt_pk_bf16_f32 v141, v198, v199
	v_cvt_pk_bf16_f32 v142, v200, v201
	v_cvt_pk_bf16_f32 v143, v202, v203
	v_cvt_pk_bf16_f32 v144, v204, v205
	v_cvt_pk_bf16_f32 v145, v206, v207
	v_cvt_pk_bf16_f32 v146, v208, v209
	v_cvt_pk_bf16_f32 v147, v210, v211
	v_cvt_pk_bf16_f32 v148, v212, v213
	v_cvt_pk_bf16_f32 v149, v214, v215
	v_cvt_pk_bf16_f32 v150, v216, v217
	v_cvt_pk_bf16_f32 v151, v218, v219
	v_cvt_pk_bf16_f32 v152, v220, v221
	v_cvt_pk_bf16_f32 v153, v222, v223
; #define MFMA32(a, b, c) __builtin_amdgcn_mfma_f32_32x32x16_bf16((a), (b), (c), 0, 0, 0)
; DI float ex2(float x) { return __builtin_amdgcn_exp2f(x); }
; template <int S> DI bf16x8 pack8(const f32x16& x) { u32x4 p; p[0] = cvtpk(x[8 * S], x[8 * S + 1]); p[1] = cvtpk(x[8 * S + 2], x[8 * S + 3]); p[2] = cvtpk(x[8 * S + 4], x[8 * S + 5]); p[3] = cvtpk(x[8 * S + 6], x[8 * S + 7]); return __builtin_bit_cast(bf16x8, p); }
; #define SB_PV(ks, pa) { const bf16x8 v0 = ldsv(Vt + off128(r32, 2 * (ks) + hi)), v1 = ldsv(Vt + off128(32 + r32, 2 * (ks) + hi)); o0 = MFMA32(v0, pa, o0); o1 = MFMA32(v1, pa, o1); }
; DI void sb_unit(LAS char* lds, int b, int h, int qb, const bf16_t* __restrict__ Q, const bf16_t* __restrict__ K, const bf16_t* __restrict__ VT, const bf16_t* __restrict__ G, bf16_t* __restrict__ MIX) {
;     ...
;             f32x16 C0 = splat16(carry), C1 = C0;
;             C0 = MFMA32(tp0, Lh0, C0); C0 = MFMA32(tp1, Lh1, C0); C0 = MFMA32(ones, Lh2, C0); C0 = MFMA32(ones, Lh3, C0);
;             C1 = MFMA32(tp0, Lh2, C1); C1 = MFMA32(tp1, Lh3, C1);
;             const float cn = C0[0] + L0[0];
;             carry = __shfl(cn, r32, 64);
; #pragma unroll
;             for (int r = 0; r < 16; ++r) { p0[r] = ex2(p0[r] + C0[r]); p1[r] = ex2(p1[r] + C1[r]); }
;             const bf16x8 pa0 = pack8<0>(p0), pa1 = pack8<1>(p0), pa2 = pack8<0>(p1), pa3 = pack8<1>(p1);
;     ...
;             SB_PV(0, pa0) SB_PV(1, pa1) SB_PV(2, pa2) SB_PV(3, pa3)
;     ...
;             done = __all(carry < -152.f) ? 1 : 0;
.Lsb_sp_join:
	v_mov_b32_e32 v35, v34
	v_mov_b64_e32 v[36:37], v[34:35]
	v_mov_b64_e32 v[38:39], v[34:35]
	v_mov_b64_e32 v[40:41], v[34:35]
	v_mov_b64_e32 v[42:43], v[34:35]
	v_mov_b64_e32 v[44:45], v[34:35]
	v_mov_b64_e32 v[46:47], v[34:35]
	v_mov_b64_e32 v[48:49], v[34:35]
	s_nop 2
	v_mfma_f32_32x32x16_bf16 v[50:65], v[84:87], v[138:141], v[34:49]
	s_mov_b32 s0, 0xc3180000
	v_mfma_f32_32x32x16_bf16 v[50:65], v[88:91], v[142:145], v[50:65]
	v_mfma_f32_32x32x16_bf16 v[34:49], v[84:87], v[146:149], v[34:49]
	v_mfma_f32_32x32x16_bf16 v[50:65], v[240:243], v[146:149], v[50:65]
	v_mfma_f32_32x32x16_bf16 v[34:49], v[88:91], v[150:153], v[34:49]
	v_mfma_f32_32x32x16_bf16 v[50:65], v[240:243], v[150:153], v[50:65]
	ds_read_b128 v[160:163], v225 offset:8192
	ds_read_b128 v[164:167], v225 offset:12288
	ds_read_b128 v[168:171], v226 offset:8192
	ds_read_b128 v[172:175], v226 offset:12288
	ds_read_b128 v[176:179], v227 offset:8192
	ds_read_b128 v[180:183], v227 offset:12288
	ds_read_b128 v[184:187], v228 offset:8192
	ds_read_b128 v[188:191], v228 offset:12288
	s_nop 4
	v_add_f32_e32 v38, v118, v38
	v_add_f32_e32 v39, v120, v39
	v_add_f32_e32 v40, v122, v40
	v_add_f32_e32 v42, v126, v42
	v_add_f32_e32 v43, v128, v43
	v_add_f32_e32 v44, v130, v44
	v_add_f32_e32 v45, v132, v45
	v_add_f32_e32 v46, v134, v46
	v_add_f32_e32 v67, v109, v50
	v_add_f32_e32 v50, v50, v108
	v_add_f32_e32 v54, v54, v117
	v_exp_f32_e32 v108, v38
	v_add_f32_e32 v38, v55, v119
	v_exp_f32_e32 v55, v39
	v_add_f32_e32 v39, v56, v121
	v_exp_f32_e32 v56, v40
	v_add_f32_e32 v40, v57, v123
	v_add_f32_e32 v57, v58, v125
	v_exp_f32_e32 v58, v42
	v_add_f32_e32 v42, v59, v127
	v_exp_f32_e32 v59, v43
	v_add_f32_e32 v43, v60, v129
	v_exp_f32_e32 v60, v44
	v_add_f32_e32 v44, v61, v131
	v_exp_f32_e32 v61, v45
	v_add_f32_e32 v45, v62, v133
	v_exp_f32_e32 v62, v46
	v_add_f32_e32 v46, v63, v135
	v_add_f32_e32 v51, v51, v111
	v_add_f32_e32 v52, v52, v113
	v_add_f32_e32 v53, v53, v115
	v_exp_f32_e32 v54, v54
	v_exp_f32_e32 v38, v38
	v_add_f32_e32 v41, v124, v41
	v_exp_f32_e32 v63, v46
	v_add_f32_e32 v46, v136, v47
	ds_bpermute_b32 v67, v229, v67
	v_exp_f32_e32 v50, v50
	v_exp_f32_e32 v51, v51
	v_exp_f32_e32 v52, v52
	v_exp_f32_e32 v53, v53
	v_exp_f32_e32 v39, v39
	v_exp_f32_e32 v40, v40
	v_exp_f32_e32 v41, v41
	v_exp_f32_e32 v57, v57
	v_exp_f32_e32 v42, v42
	v_exp_f32_e32 v109, v46
	v_add_f32_e32 v46, v64, v66
	v_exp_f32_e32 v64, v46
	v_add_f32_e32 v46, v154, v48
	v_exp_f32_e32 v66, v46
	v_add_f32_e32 v46, v65, v155
	v_exp_f32_e32 v65, v46
	v_add_f32_e32 v46, v156, v49
	v_cvt_pk_bf16_f32 v48, v54, v38
	v_add_f32_e32 v34, v110, v34
	v_exp_f32_e32 v110, v46
	v_cvt_pk_bf16_f32 v46, v50, v51
	v_cvt_pk_bf16_f32 v47, v52, v53
	v_cvt_pk_bf16_f32 v49, v39, v40
	v_cvt_pk_bf16_f32 v42, v57, v42
	v_cvt_pk_bf16_f32 v40, v108, v55
	v_cvt_pk_bf16_f32 v41, v56, v41
	s_waitcnt lgkmcnt(0)
	v_mfma_f32_32x32x16_bf16 v[18:33], v[160:163], v[46:49], v[18:33]
	v_exp_f32_e32 v43, v43
	v_exp_f32_e32 v44, v44
	v_exp_f32_e32 v45, v45
	v_add_f32_e32 v35, v112, v35
	v_add_f32_e32 v36, v114, v36
	v_cvt_pk_bf16_f32 v43, v43, v44
	s_waitcnt lgkmcnt(0)
	v_mfma_f32_32x32x16_bf16 v[2:17], v[164:167], v[46:49], v[2:17]
	v_cvt_pk_bf16_f32 v44, v45, v63
	v_cvt_pk_bf16_f32 v45, v64, v65
	v_add_f32_e32 v37, v116, v37
	v_exp_f32_e32 v34, v34
	v_exp_f32_e32 v35, v35
	v_exp_f32_e32 v36, v36
	s_waitcnt lgkmcnt(1)
	v_mfma_f32_32x32x16_bf16 v[18:33], v[168:171], v[42:45], v[18:33]
	v_exp_f32_e32 v37, v37
	v_cvt_pk_bf16_f32 v38, v34, v35
	v_cvt_pk_bf16_f32 v34, v58, v59
	v_cvt_pk_bf16_f32 v35, v60, v61
	v_cvt_pk_bf16_f32 v39, v36, v37
	v_cvt_pk_bf16_f32 v36, v62, v109
	s_waitcnt lgkmcnt(0)
	v_mfma_f32_32x32x16_bf16 v[2:17], v[172:175], v[42:45], v[2:17]
	v_cvt_pk_bf16_f32 v37, v66, v110
	v_cmp_gt_f32_e32 vcc, s0, v67
	s_cmp_eq_u64 vcc, exec
	s_cselect_b64 s[0:1], -1, 0
	s_waitcnt lgkmcnt(1)
	v_mfma_f32_32x32x16_bf16 v[18:33], v[176:179], v[38:41], v[18:33]
	s_waitcnt lgkmcnt(0)
	v_mfma_f32_32x32x16_bf16 v[2:17], v[180:183], v[38:41], v[2:17]
	s_waitcnt lgkmcnt(1)
	v_mfma_f32_32x32x16_bf16 v[18:33], v[184:187], v[34:37], v[18:33]
	s_waitcnt lgkmcnt(0)
	v_mfma_f32_32x32x16_bf16 v[2:17], v[188:191], v[34:37], v[2:17]
	v_cndmask_b32_e64 v36, 0, 1, s[0:1]
	v_mov_b32_e32 v34, v67
